# P2 context K|V tile: all 24 fragment loads issued up front (were drip-fed with a wait before almost every MFMA)
# speedup vs baseline: 1.0177x; 1.0005x over previous
; #define LAS __attribute__((address_space(3)))
; #define LDS_WAIT() asm volatile("s_waitcnt lgkmcnt(0)" ::: "memory")
; #define MFMA32(a, b, c) __builtin_amdgcn_mfma_f32_32x32x16_bf16((a), (b), (c), 0, 0, 0)
; __device__ __forceinline__ void ctx_tile(const Ptrs& P, LAS unsigned char* lds, int tile, int tid, int wave, int lane) {
;     ...
;     const bf16_t* A = (const bf16_t*)(ws + WS_H) + (size_t)(MTOK + 32 * trow + r) * DM + 128 * wave + 8 * hh;
;     const bf16_t* Bw = (const bf16_t*)(ws + WS_WIN) + (size_t)(tcol < 4 ? 1024 + 32 * tcol + r : 1024 + 64 * tcol + r) * DM + 128 * wave + 8 * hh; const int bstep = tcol < 4 ? 128 : 32;
;     f32x16 acc[2];
; #pragma unroll
;     for (int j = 0; j < 2; ++j)
; #pragma unroll
;         for (int i = 0; i < 16; ++i) acc[j][i] = 0.f;
; #pragma unroll
;     for (int ks = 0; ks < 8; ++ks) { const bf16x8_t a = *(const bf16x8_t*)(A + 16 * ks);
; #pragma unroll
;         for (int j = 0; j < 2; ++j) { const bf16x8_t b = *(const bf16x8_t*)(Bw + (size_t)bstep * j * DM + 16 * ks); acc[j] = MFMA32(a, b, acc[j]); } }
;     LAS float* red = (LAS float*)lds;
; #pragma unroll
;     for (int j = 0; j < 2; ++j)
; #pragma unroll
;         for (int i = 0; i < 16; ++i) red[(wave * 32 + j * 16 + i) * 64 + lane] = acc[j][i];
;     LDS_WAIT(); __builtin_amdgcn_s_barrier(); asm volatile("" ::: "memory");
;     {
;         const int row = tid >> 4, c = (tid & 15) * 4, cb = c >> 5, i = (row & 3) + 4 * (row >> 3), ln = (c & 31) + 32 * ((row >> 2) & 1);
;         f32x4 s = {0.f, 0.f, 0.f, 0.f};
; #pragma unroll
;         for (int w = 0; w < 8; ++w) s += *(const LAS f32x4*)(red + (w * 32 + cb * 16 + i) * 64 + ln);
.LBB9_210:
	s_and_b32 s21, s19, 7
	s_and_b32 s22, s12, 0xffffffe0
	s_cmp_lt_u32 s21, 4
	s_cselect_b64 s[2:3], -1, 0
	s_lshl_b32 s0, s21, 5
	s_lshl_b32 s20, s21, 6
	s_and_b64 s[2:3], s[2:3], exec
	s_cselect_b32 s0, s0, s20
	v_add_u32_e32 v0, s22, v51
	v_or_b32_e32 v2, s0, v50
	v_ashrrev_i32_e32 v1, 31, v0
	v_lshlrev_b32_e32 v32, 11, v2
	v_lshlrev_b64 v[0:1], 11, v[0:1]
	v_lshl_add_u64 v[2:3], s[90:91], 0, v[32:33]
	v_lshl_add_u64 v[2:3], v[2:3], 0, s[8:9]
	v_lshl_add_u64 v[42:43], v[34:35], 0, v[0:1]
	s_waitcnt lgkmcnt(3)
	v_lshl_add_u64 v[8:9], v[2:3], 0, v[38:39]
	global_load_dwordx4 v[88:91], v[42:43], off
	v_add_co_u32_e32 v4, vcc, s17, v8
	s_cselect_b32 s0, s16, 0x10000
	s_nop 0
	v_addc_co_u32_e32 v5, vcc, 0, v9, vcc
	global_load_dwordx4 v[92:95], v[4:5], off
	v_lshl_add_u64 v[80:81], v[8:9], 0, s[10:11]
	v_lshl_add_u64 v[84:85], v[80:81], 0, s[0:1]
	global_load_dwordx4 v[96:99], v[42:43], off offset:32
	global_load_dwordx4 v[100:103], v[80:81], off offset:224
	s_cmp_gt_u32 s21, 3
	s_mov_b64 s[2:3], -1
	global_load_dwordx4 v[104:107], v[84:85], off
	global_load_dwordx4 v[108:111], v[84:85], off offset:32
	global_load_dwordx4 v[112:115], v[80:81], off offset:32
	global_load_dwordx4 v[116:119], v[80:81], off offset:64
	global_load_dwordx4 v[120:123], v[42:43], off offset:64
	global_load_dwordx4 v[124:127], v[42:43], off offset:96
	global_load_dwordx4 v[128:131], v[84:85], off offset:64
	global_load_dwordx4 v[132:135], v[84:85], off offset:96
	global_load_dwordx4 v[136:139], v[80:81], off offset:96
	global_load_dwordx4 v[140:143], v[80:81], off offset:128
	global_load_dwordx4 v[144:147], v[42:43], off offset:128
	global_load_dwordx4 v[148:151], v[42:43], off offset:160
	global_load_dwordx4 v[210:213], v[84:85], off offset:128
	global_load_dwordx4 v[214:217], v[84:85], off offset:160
	global_load_dwordx4 v[218:221], v[80:81], off offset:160
	global_load_dwordx4 v[222:225], v[80:81], off offset:192
	global_load_dwordx4 v[226:229], v[42:43], off offset:192
	global_load_dwordx4 v[230:233], v[84:85], off offset:192
	global_load_dwordx4 v[234:237], v[42:43], off offset:224
	global_load_dwordx4 v[238:241], v[84:85], off offset:224
	v_add_u32_e32 v42, s22, v52
	s_waitcnt lgkmcnt(0)
	s_waitcnt vmcnt(22)
	v_mfma_f32_32x32x16_bf16 v[16:31], v[88:91], v[92:95], 0
	s_waitcnt vmcnt(19)
	v_mfma_f32_32x32x16_bf16 v[0:15], v[88:91], v[104:107], 0
	s_waitcnt vmcnt(17)
	v_mfma_f32_32x32x16_bf16 v[16:31], v[96:99], v[112:115], v[16:31]
	s_waitcnt vmcnt(18)
	v_mfma_f32_32x32x16_bf16 v[0:15], v[96:99], v[108:111], v[0:15]
	s_waitcnt vmcnt(15)
	v_mfma_f32_32x32x16_bf16 v[16:31], v[120:123], v[116:119], v[16:31]
	s_waitcnt vmcnt(13)
	v_mfma_f32_32x32x16_bf16 v[0:15], v[120:123], v[128:131], v[0:15]
	s_waitcnt vmcnt(12)
	v_mfma_f32_32x32x16_bf16 v[0:15], v[124:127], v[132:135], v[0:15]
	s_waitcnt vmcnt(11)
	v_mfma_f32_32x32x16_bf16 v[16:31], v[124:127], v[136:139], v[16:31]
	s_waitcnt vmcnt(9)
	v_mfma_f32_32x32x16_bf16 v[16:31], v[144:147], v[140:143], v[16:31]
	s_waitcnt vmcnt(7)
	v_mfma_f32_32x32x16_bf16 v[0:15], v[144:147], v[210:213], v[0:15]
	s_waitcnt vmcnt(6)
	v_mfma_f32_32x32x16_bf16 v[0:15], v[148:151], v[214:217], v[0:15]
	s_waitcnt vmcnt(5)
	v_mfma_f32_32x32x16_bf16 v[16:31], v[148:151], v[218:221], v[16:31]
	s_waitcnt vmcnt(3)
	v_mfma_f32_32x32x16_bf16 v[16:31], v[226:229], v[222:225], v[16:31]
	s_waitcnt vmcnt(2)
	v_mfma_f32_32x32x16_bf16 v[0:15], v[226:229], v[230:233], v[0:15]
	s_waitcnt vmcnt(1)
	v_mfma_f32_32x32x16_bf16 v[16:31], v[234:237], v[100:103], v[16:31]
	s_waitcnt vmcnt(0)
	v_mfma_f32_32x32x16_bf16 v[0:15], v[234:237], v[238:241], v[0:15]
	s_nop 9
	ds_write2st64_b32 v55, v16, v17 offset1:1
	ds_write2st64_b32 v55, v18, v19 offset0:2 offset1:3
	ds_write2st64_b32 v55, v20, v21 offset0:4 offset1:5
	ds_write2st64_b32 v55, v22, v23 offset0:6 offset1:7
	ds_write2st64_b32 v55, v24, v25 offset0:8 offset1:9
	ds_write2st64_b32 v55, v26, v27 offset0:10 offset1:11
	ds_write2st64_b32 v55, v28, v29 offset0:12 offset1:13
	ds_write2st64_b32 v55, v30, v31 offset0:14 offset1:15
	ds_write2st64_b32 v55, v0, v1 offset0:16 offset1:17
	ds_write2st64_b32 v55, v2, v3 offset0:18 offset1:19
	ds_write2st64_b32 v55, v4, v5 offset0:20 offset1:21
	ds_write2st64_b32 v55, v6, v7 offset0:22 offset1:23
	ds_write2st64_b32 v55, v8, v9 offset0:24 offset1:25
	ds_write2st64_b32 v55, v10, v11 offset0:26 offset1:27
	ds_write2st64_b32 v55, v12, v13 offset0:28 offset1:29
	ds_write2st64_b32 v55, v14, v15 offset0:30 offset1:31
	s_waitcnt lgkmcnt(0)
	s_barrier
	ds_read_b128 v[0:3], v56
	ds_read_b128 v[4:7], v56 offset:8192
	ds_read_b128 v[8:11], v56 offset:16384
	ds_read_b128 v[12:15], v56 offset:24576
	ds_read_b128 v[16:19], v56 offset:32768
	ds_read_b128 v[20:23], v56 offset:40960
	ds_read_b128 v[24:27], v56 offset:49152
	ds_read_b128 v[28:31], v56 offset:57344
	s_waitcnt lgkmcnt(7)
	v_pk_add_f32 v[2:3], v[2:3], 0 op_sel_hi:[1,0]
	v_pk_add_f32 v[0:1], v[0:1], 0 op_sel_hi:[1,0]
	s_waitcnt lgkmcnt(6)
	v_pk_add_f32 v[2:3], v[2:3], v[6:7]
	v_pk_add_f32 v[0:1], v[0:1], v[4:5]
	s_waitcnt lgkmcnt(5)
	v_pk_add_f32 v[2:3], v[2:3], v[10:11]
	v_pk_add_f32 v[0:1], v[0:1], v[8:9]
	s_waitcnt lgkmcnt(4)
	v_pk_add_f32 v[2:3], v[2:3], v[14:15]
	v_pk_add_f32 v[0:1], v[0:1], v[12:13]
	s_waitcnt lgkmcnt(3)
	v_pk_add_f32 v[2:3], v[2:3], v[18:19]
	v_pk_add_f32 v[0:1], v[0:1], v[16:17]
	s_waitcnt lgkmcnt(2)
	v_pk_add_f32 v[2:3], v[2:3], v[22:23]
	v_pk_add_f32 v[0:1], v[0:1], v[20:21]
	s_waitcnt lgkmcnt(1)
	v_pk_add_f32 v[2:3], v[2:3], v[26:27]
	v_pk_add_f32 v[4:5], v[0:1], v[24:25]
	s_waitcnt lgkmcnt(0)
	v_pk_add_f32 v[0:1], v[2:3], v[30:31]
	v_pk_add_f32 v[2:3], v[4:5], v[28:29]
	s_cbranch_scc0 .LBB9_212
	v_and_b32_e32 v4, 0xffffff00, v42
	v_add3_u32 v4, v53, s20, v4
	v_ashrrev_i32_e32 v5, 31, v4
	v_lshlrev_b64 v[4:5], 9, v[4:5]
	v_and_or_b32 v6, v42, s18, v54
	v_lshl_add_u64 v[4:5], s[4:5], 0, v[4:5]
	v_lshlrev_b32_e32 v32, 1, v6
	v_lshl_add_u64 v[4:5], v[4:5], 0, v[32:33]
	v_cvt_pk_bf16_f32 v6, v2, s0
	global_store_short v[4:5], v6, off
	v_cvt_pk_bf16_f32 v6, v3, s0
	global_store_short v[4:5], v6, off offset:512
	v_cvt_pk_bf16_f32 v6, v0, s0
	global_store_short v[4:5], v6, off offset:1024
	v_cvt_pk_bf16_f32 v6, v1, s0
	global_store_short v[4:5], v6, off offset:1536
	s_mov_b64 s[2:3], 0
